# strategy 4: static s_setprio 1 for the RWKV prep waves (waves 4-7) for the whole scan phase, reset at phase exit
# baseline (speedup 1.0000x reference)
; __device__ __forceinline__ int ltid() { int t = threadIdx.x; asm volatile("" : "+v"(t)); return t; }
; __device__ __forceinline__ int lsg(int x) { x = __builtin_amdgcn_readfirstlane(x); asm volatile("" : "+s"(x)); return x; }
; __device__ __forceinline__ void phase_rwkv(KP P, int l_, unsigned char* shm) {
;     const int l = lsg(l_);
;     const int tid = ltid(), wave = __builtin_amdgcn_readfirstlane(tid >> 6), lane = tid & 63;
;     const int rp = (tid & 255) >> 3, seg = tid & 7, pw = wave & 3;
;     const bool scanw = wave < 4;
;     const u16* pB = (const u16*)(P->ws + WS_P);
;     const u16* LO = (const u16*)(P->ws + WS_LO);
;     u16* OB = (u16*)(P->ws + WS_O);
;     constexpr int T = 32, NC = SEQ / T, CS = 5 * T * 64;
;     float* sCoef = (float*)shm;
;     float* sV = sCoef + 2 * CS;
;     float* sG = sV + 3 * T * 64;
;     float* sO = sG + 2 * T * 64;
;     float* sBon = sO + 2 * T * 64;
;     for (int bh = blockIdx.x; bh < 256; bh += gridDim.x) {
;         const int b = bh >> 3, h = bh & 7, ch = h * 64 + lane;
;         const float mu_r = P->in[14][(size_t)l * 1824 + ch], mu_k = P->in[14][(size_t)l * 1824 + 512 + ch], mu_v = P->in[14][(size_t)l * 1824 + 1024 + ch];
;         const float kkw = P->in[20][(size_t)l * 512 + ch], kaw = P->in[21][(size_t)l * 512 + ch], rkw = P->in[22][(size_t)l * 512 + ch];
;         const float lnw = P->in[23][(size_t)l * 512 + ch], lnb = P->in[24][(size_t)l * 512 + ch];
;         const float w0c = P->in[15][(size_t)l * 512 + ch], a0c = P->in[17][(size_t)l * 512 + ch];
;         f32x2 sa[4], sb[4];
; #pragma unroll
;         for (int jj = 0; jj < 4; ++jj) { sa[jj] = (f32x2){0.f, 0.f}; sb[jj] = (f32x2){0.f, 0.f}; }
;         unsigned short gr[9], gk[9], gv[9], gw[8], ga[8], gg[8];
.LBB0_2460:
	s_or_b64 exec, exec, s[4:5]
	v_readlane_b32 s0, v255, 1
	s_mov_b32 s4, s0
	v_readlane_b32 s0, v254, 1
	s_mov_b64 s[6:7], s[72:73]
	s_waitcnt lgkmcnt(0)
	v_mov_b32_e32 v0, v228
	v_readlane_b32 s1, v254, 2
	s_barrier
	s_and_b64 vcc, exec, s[0:1]
	v_readfirstlane_b32 s5, v0
	s_cbranch_vccz .LBB0_2529
	s_load_dwordx2 s[8:9], s[6:7], 0xf8
	s_load_dwordx2 s[22:23], s[6:7], 0xc0
	s_ashr_i32 s0, s5, 6
	s_cmp_gt_i32 s0, 3
	s_cselect_b64 s[20:21], -1, 0
	s_cbranch_scc0 .Lrw_prio_skip
	s_setprio 1
.Lrw_prio_skip:
	s_waitcnt lgkmcnt(0)
	s_add_u32 s24, s8, 0x17b00000
	s_addc_u32 s25, s9, 0
	s_add_u32 s26, s8, 0x2bb00000
	s_addc_u32 s27, s9, 0
	s_add_u32 s28, s8, 0x27b00000
	s_addc_u32 s29, s9, 0
	s_load_dwordx4 s[16:19], s[6:7], 0x70
	s_load_dwordx2 s[30:31], s[6:7], 0x88
	s_load_dwordx8 s[8:15], s[6:7], 0xa0
	s_ashr_i32 s5, s4, 31
	s_mul_i32 s6, s4, 0x1c80
	s_mul_hi_i32 s1, s4, 0x1c80
	s_waitcnt lgkmcnt(0)
	s_add_u32 s16, s16, s6
	s_addc_u32 s17, s17, s1
	s_add_u32 s34, s16, 0x1000
	s_addc_u32 s35, s17, 0
	s_lshl_b32 s0, s0, 3
	v_and_b32_e32 v122, 63, v0
	s_and_b32 s38, s0, 24
	v_lshl_or_b32 v1, s38, 6, v122
	s_or_b32 s96, s38, 1
	v_lshlrev_b32_e32 v124, 2, v1
	v_lshl_or_b32 v1, s96, 6, v122
	s_or_b32 s48, s38, 2
	v_lshlrev_b32_e32 v128, 2, v1
	v_lshl_or_b32 v1, s48, 6, v122
	s_or_b32 s60, s38, 3
	s_or_b32 s0, s38, 32
	v_sub_co_u32_e64 v4, s[42:43], s38, 1
	v_lshlrev_b32_e32 v132, 2, v1
	v_lshl_or_b32 v1, s60, 6, v122
	s_or_b32 s54, s38, 4
	v_writelane_b32 v255, s0, 13
	s_xor_b64 s[0:1], s[42:43], -1
	v_readlane_b32 s43, v254, 31
	s_lshl_b32 s42, s96, 2
	v_lshlrev_b32_e32 v136, 2, v1
	v_lshl_or_b32 v1, s54, 6, v122
	s_or_b32 s74, s38, 5
	v_writelane_b32 v255, s0, 14
	s_add_i32 s62, s43, s42
	s_lshl_b32 s42, s48, 2
	v_lshlrev_b32_e32 v140, 2, v1
	v_lshl_or_b32 v1, s74, 6, v122
	s_or_b32 s76, s38, 6
	v_writelane_b32 v255, s1, 15
	s_lshl_b32 s0, s38, 12
	s_mov_b32 s1, s53
	s_add_i32 s63, s43, s42
	s_lshl_b32 s42, s60, 2
	v_lshlrev_b32_e32 v144, 2, v1
	v_lshl_or_b32 v1, s76, 6, v122
	s_or_b32 s80, s38, 7
	v_writelane_b32 v255, s0, 16
	s_add_i32 s64, s43, s42
	s_lshl_b32 s42, s54, 2
	v_lshlrev_b32_e32 v148, 2, v1
	v_lshl_or_b32 v1, s80, 6, v122
	v_writelane_b32 v255, s1, 17
	s_add_i32 s0, 0, 0x14000
	s_add_i32 s65, s43, s42
	s_lshl_b32 s42, s74, 2
	v_lshlrev_b32_e32 v152, 2, v1
	v_add_u32_e32 v126, s0, v124
	s_add_i32 s1, 0, 0x1a000
	s_lshl_b32 s41, s38, 2
	v_add_u32_e32 v130, s0, v128
	v_add_u32_e32 v134, s0, v132
	v_add_u32_e32 v138, s0, v136
	v_add_u32_e32 v142, s0, v140
	v_add_u32_e32 v146, s0, v144
	s_add_i32 s58, s43, s42
	v_add_u32_e32 v150, s0, v148
	s_lshl_b32 s42, s76, 2
	v_add_u32_e32 v154, s0, v152
	s_lshl_b32 s0, s80, 2
	s_lshl_b64 s[36:37], s[4:5], 9
	s_or_b32 s40, s38, 64
	v_add_u32_e32 v127, s1, v124
	s_add_i32 s41, s43, s41
	v_add_u32_e32 v131, s1, v128
	v_add_u32_e32 v135, s1, v132
	v_add_u32_e32 v139, s1, v136
	v_add_u32_e32 v143, s1, v140
	v_add_u32_e32 v147, s1, v144
	v_add_u32_e32 v151, s1, v148
	s_add_i32 s59, s43, s42
	v_add_u32_e32 v155, s1, v152
	s_add_i32 s56, s43, s0
	s_add_i32 s0, 0, 0x1c000
	s_lshl_b32 s1, s38, 10
	s_add_u32 s50, s28, s1
	s_addc_u32 s51, s29, 0
	v_writelane_b32 v255, s50, 18
	s_lshl_b32 s1, s96, 10
	v_add_u32_e32 v158, s0, v124
	v_writelane_b32 v255, s51, 19
	s_add_u32 s50, s28, s1
	s_addc_u32 s51, s29, 0
	v_writelane_b32 v255, s50, 20
	s_lshl_b32 s1, s48, 10
	v_add_u32_e32 v160, s0, v128
	v_writelane_b32 v255, s51, 21
	s_add_u32 s50, s28, s1
	s_addc_u32 s51, s29, 0
	v_writelane_b32 v255, s50, 22
	s_lshl_b32 s1, s60, 10
	v_add_u32_e32 v162, s0, v132
	v_writelane_b32 v255, s51, 23
	s_add_u32 s50, s28, s1
	s_addc_u32 s51, s29, 0
	v_writelane_b32 v255, s50, 24
	s_lshl_b32 s1, s54, 10
	v_add_u32_e32 v164, s0, v136
	v_writelane_b32 v255, s51, 25
	s_add_u32 s50, s28, s1
	s_addc_u32 s51, s29, 0
	v_writelane_b32 v255, s50, 26
	s_lshl_b32 s1, s74, 10
	v_add_u32_e32 v166, s0, v140
	v_writelane_b32 v255, s51, 27
	s_add_u32 s50, s28, s1
	s_addc_u32 s51, s29, 0
	v_writelane_b32 v255, s50, 28
	s_lshl_b32 s1, s76, 10
	v_add_u32_e32 v168, s0, v144
	v_writelane_b32 v255, s51, 29
	s_add_u32 s50, s28, s1
	v_add_u32_e32 v170, s0, v148
	s_addc_u32 s51, s29, 0
	v_add_u32_e32 v172, s0, v152
	s_lshl_b32 s0, s80, 10
	v_writelane_b32 v255, s50, 30
	s_add_u32 s0, s28, s0
	v_bfe_u32 v123, v0, 3, 5
	v_and_b32_e32 v0, 7, v0
	v_writelane_b32 v255, s51, 31
	s_addc_u32 s1, s29, 0
	v_cmp_eq_u32_e64 s[6:7], 0, v0
	v_lshlrev_b32_e32 v0, 5, v0
	v_readlane_b32 s42, v254, 32
	v_writelane_b32 v255, s0, 32
	v_lshlrev_b32_e32 v173, 2, v123
	v_mov_b64_e32 v[188:189], 0x15ff
	s_mov_b32 s39, s53
	v_cmp_eq_u32_e64 s[4:5], 0, v122
	v_lshlrev_b64 v[82:83], 12, v[4:5]
	v_add_u32_e32 v125, 0, v124
	v_add_u32_e32 v129, 0, v128
	v_add_u32_e32 v133, 0, v132
	v_add_u32_e32 v137, 0, v136
	v_add_u32_e32 v141, 0, v140
	v_add_u32_e32 v145, 0, v144
	v_add_u32_e32 v149, 0, v148
	v_add_u32_e32 v153, 0, v152
	s_mov_b32 s97, s53
	s_mov_b32 s49, s53
	s_mov_b32 s61, s53
	s_mov_b32 s55, s53
	s_mov_b32 s75, s53
	s_mov_b32 s77, s53
	s_mov_b32 s81, s53
	v_add_u32_e32 v156, 0, v0
	v_add_u32_e32 v157, s42, v124
	v_add_u32_e32 v159, s42, v128
	v_add_u32_e32 v161, s42, v132
	v_add_u32_e32 v163, s42, v136
	v_add_u32_e32 v165, s42, v140
	v_add_u32_e32 v167, s42, v144
	v_add_u32_e32 v169, s42, v148
	v_add_u32_e32 v171, s42, v152
	v_writelane_b32 v255, s1, 33
	v_or_b32_e32 v174, 0x100, v0
	v_or_b32_e32 v239, 0x14100, v173
	v_mov_b32_e32 v176, 0
	v_mov_b32_e32 v221, 0
	s_mov_b32 s57, s2
	v_mov_b32_e32 v223, 0
	v_mov_b32_e32 v224, 0
	v_mov_b32_e32 v225, 0
	v_mov_b32_e32 v222, 0
	v_mov_b32_e32 v226, 0
	v_mov_b32_e32 v227, 0
	v_mov_b32_e32 v242, 0
	v_mov_b32_e32 v214, 0
	v_mov_b32_e32 v215, 0
	v_mov_b32_e32 v216, 0
	v_mov_b32_e32 v217, 0
	v_mov_b32_e32 v218, 0
	v_mov_b32_e32 v219, 0
	s_branch .LBB0_2463

; __device__ __forceinline__ unsigned xb_ld(unsigned* p)              { return __hip_atomic_load(p, __ATOMIC_RELAXED, __HIP_MEMORY_SCOPE_AGENT); }
; __device__ __forceinline__ unsigned xb_add(unsigned* p, unsigned v) { return __hip_atomic_fetch_add(p, v, __ATOMIC_RELAXED, __HIP_MEMORY_SCOPE_AGENT); }
; #define XB_SPIN(cond, bar) do { unsigned _sp = 0; while (cond) { __builtin_amdgcn_s_sleep(1); \
;     if ((++_sp & 255u) == 0u) { if (xb_ld(&(bar)[XB_TMO])) break; if (_sp > XB_SPIN_CAP) { atomicAdd(&(bar)[XB_TMO], 1u); break; } } } } while (0)
; __device__ __forceinline__ void xcd_barrier(const XcdBarrier& b) {
;     asm volatile("s_waitcnt vmcnt(0)" ::: "memory");
;     __syncthreads();
;     if (threadIdx.x == 0) {
;         unsigned* bar = b.bar;
;         __builtin_amdgcn_s_waitcnt(0);
;         unsigned nloc = b.st[0], nx = b.st[1];
;         if (nloc == 0u) { xcd_barrier_complete(bar, b.x, nloc, nx); b.st[0] = nloc; b.st[1] = nx; }
;         const unsigned old = xb_add(&bar[XB_XSUB(b.x)], 1u);
;         const unsigned gen = old / nloc;
;         if (old + 1u == (gen + 1u) * nloc) {
;             __builtin_amdgcn_fence(__ATOMIC_RELEASE, "agent");
;             asm volatile("s_waitcnt vmcnt(0)" ::: "memory");
;             const unsigned og = xb_add(&bar[XB_TOP], 1u);
;             const unsigned tg = og / nx;
;             if (og + 1u == (tg + 1u) * nx) xb_add(&bar[XB_TOPGEN], 1u);
;             else XB_SPIN(xb_ld(&bar[XB_TOPGEN]) == tg, bar);
;             __builtin_amdgcn_fence(__ATOMIC_ACQUIRE, "agent");
;             xb_add(&bar[XB_XGEN(b.x)], 1u);
;             asm volatile("s_waitcnt vmcnt(0)" ::: "memory");
;         } else {
;             XB_SPIN(xb_ld(&bar[XB_XGEN(b.x)]) == gen, bar);
;             __builtin_amdgcn_fence(__ATOMIC_ACQUIRE, "agent");
;             asm volatile("s_waitcnt vmcnt(0)" ::: "memory");
;         }
;     }
;     __syncthreads();
; }
.LBB0_2529:
	s_setprio 0
	s_mov_b64 s[6:7], s[72:73]
	s_getreg_b32 s8, hwreg(HW_REG_XCC_ID, 0, 4)
	s_waitcnt vmcnt(0)
	s_barrier
	s_and_saveexec_b64 s[4:5], s[70:71]
	s_cbranch_execz .LBB0_2581
	v_readlane_b32 s0, v254, 26
	s_load_dwordx2 s[6:7], s[6:7], 0xf8
	s_waitcnt vmcnt(0) expcnt(0) lgkmcnt(0)
	v_mov_b32_e32 v0, s0
	ds_read_b32 v2, v0
	v_readlane_b32 s0, v254, 27
	s_and_b32 s52, s8, 15
	s_waitcnt lgkmcnt(0)
	v_cmp_ne_u32_e32 vcc, 0, v2
	v_mov_b32_e32 v0, s0
	ds_read_b32 v0, v0
	s_cbranch_vccnz .LBB0_2545
	s_add_u32 s8, s6, 0x7ac0200
	s_addc_u32 s9, s7, 0
	s_add_u32 s10, s6, 0x7ac0400
	s_addc_u32 s11, s7, 0
	s_add_u32 s12, s6, 0x7ac0500
	s_addc_u32 s13, s7, 0
	s_add_u32 s14, s6, 0x7ac0600
	s_addc_u32 s15, s7, 0
	s_add_u32 s16, s6, 0x7ac0700
	s_addc_u32 s17, s7, 0
	s_add_u32 s18, s6, 0x7ac0800
	s_addc_u32 s19, s7, 0
	s_add_u32 s20, s6, 0x7ac0900
	s_addc_u32 s21, s7, 0
	s_add_u32 s22, s6, 0x7ac0a00
	s_addc_u32 s23, s7, 0
	s_add_u32 s24, s6, 0x7ac0b00
	s_addc_u32 s25, s7, 0
	s_add_u32 s26, s6, 0x7ac0c00
	s_addc_u32 s27, s7, 0
	s_add_u32 s28, s6, 0x7ac0d00
	s_addc_u32 s29, s7, 0
	s_add_u32 s30, s6, 0x7ac0e00
	s_addc_u32 s31, s7, 0
	s_add_u32 s34, s6, 0x7ac0f00
	s_addc_u32 s35, s7, 0
	s_add_u32 s36, s6, 0x7ac1000
	s_addc_u32 s37, s7, 0
	s_add_u32 s38, s6, 0x7ac1100
	s_addc_u32 s39, s7, 0
	s_add_u32 s40, s6, 0x7ac1200
	s_addc_u32 s41, s7, 0
	s_add_u32 s42, s6, 0x7ac1300
	s_addc_u32 s43, s7, 0
	s_mov_b32 s56, 1
	s_branch .LBB0_2533
